# GEMM accumulator zero-init with 64 v_mov_b64 instead of 128 v_mov_b32 per tile
# speedup vs baseline: 1.0057x; 1.0057x over previous
; template <class Epi>
; __device__ __forceinline__ void gemm_phase(LAS unsigned char* lds, const Gemm g, const StaticOrder& S, const Epi& E) {
;     ...
;       const char* a1 = cA + (size_t)(t + 1) * kstep;
;       const char* a2 = last ? nA : cA + (size_t)(t + 2) * kstep; const char* b2 = last ? nB : cB + (size_t)(t + 2) * kstep;
;       const char* a3 = a2 + kstep; const char* b3 = b2 + kstep;
;     ...
; #pragma unroll
;     for (int a = 0; a < 2; ++a)
; #pragma unroll
;       for (int b = 0; b < 2; ++b)
; #pragma unroll
;         for (int m = 0; m < 4; ++m)
; #pragma unroll
;           for (int n = 0; n < 2; ++n) acc[a][b][m][n] = (f32x4){0.f, 0.f, 0.f, 0.f};
;     cur = nxt; cA = nA; cB = nB; ++ui;
.LBB0_55:
	s_add_u32 s74, s12, 0x100
	s_addc_u32 s75, s13, 0
	s_add_u32 s0, s10, 0x80
	v_mov_b64_e32 v[0:1], 0
	v_mov_b64_e32 v[2:3], 0
	v_mov_b64_e32 v[4:5], 0
	v_mov_b64_e32 v[6:7], 0
	v_mov_b64_e32 v[8:9], 0
	v_mov_b64_e32 v[10:11], 0
	v_mov_b64_e32 v[12:13], 0
	v_mov_b64_e32 v[14:15], 0
	v_mov_b64_e32 v[16:17], 0
	v_mov_b64_e32 v[18:19], 0
	v_mov_b64_e32 v[20:21], 0
	v_mov_b64_e32 v[22:23], 0
	v_mov_b64_e32 v[24:25], 0
	v_mov_b64_e32 v[26:27], 0
	v_mov_b64_e32 v[28:29], 0
	v_mov_b64_e32 v[30:31], 0
	v_mov_b64_e32 v[32:33], 0
	v_mov_b64_e32 v[34:35], 0
	v_mov_b64_e32 v[36:37], 0
	v_mov_b64_e32 v[38:39], 0
	v_mov_b64_e32 v[40:41], 0
	v_mov_b64_e32 v[42:43], 0
	v_mov_b64_e32 v[44:45], 0
	v_mov_b64_e32 v[46:47], 0
	v_mov_b64_e32 v[48:49], 0
	v_mov_b64_e32 v[50:51], 0
	v_mov_b64_e32 v[52:53], 0
	v_mov_b64_e32 v[54:55], 0
	v_mov_b64_e32 v[56:57], 0
	v_mov_b64_e32 v[58:59], 0
	v_mov_b64_e32 v[60:61], 0
	v_mov_b64_e32 v[62:63], 0
	v_mov_b64_e32 v[64:65], 0
	v_mov_b64_e32 v[66:67], 0
	v_mov_b64_e32 v[68:69], 0
	v_mov_b64_e32 v[70:71], 0
	v_mov_b64_e32 v[72:73], 0
	v_mov_b64_e32 v[74:75], 0
	v_mov_b64_e32 v[76:77], 0
	v_mov_b64_e32 v[78:79], 0
	v_mov_b64_e32 v[82:83], 0
	v_mov_b64_e32 v[84:85], 0
	v_mov_b64_e32 v[86:87], 0
	v_mov_b64_e32 v[88:89], 0
	v_mov_b64_e32 v[90:91], 0
	v_mov_b64_e32 v[92:93], 0
	v_mov_b64_e32 v[94:95], 0
	v_mov_b64_e32 v[96:97], 0
	v_mov_b64_e32 v[98:99], 0
	v_mov_b64_e32 v[100:101], 0
	v_mov_b64_e32 v[102:103], 0
	v_mov_b64_e32 v[104:105], 0
	v_mov_b64_e32 v[106:107], 0
	v_mov_b64_e32 v[108:109], 0
	v_mov_b64_e32 v[110:111], 0
	v_mov_b64_e32 v[112:113], 0
	v_mov_b64_e32 v[114:115], 0
	v_mov_b64_e32 v[116:117], 0
	v_mov_b64_e32 v[118:119], 0
	v_mov_b64_e32 v[120:121], 0
	v_mov_b64_e32 v[122:123], 0
	v_mov_b64_e32 v[124:125], 0
	v_mov_b64_e32 v[126:127], 0
	v_mov_b64_e32 v[128:129], 0
	s_addc_u32 s1, s11, 0
	s_mov_b32 s10, 0
